# down-projection epilogue: column scales + eight row scales prefetched before the K-loop (serial load/vmcnt(0) chain removed), on top of v26
# baseline (speedup 1.0000x reference)
.LBB0_1098:
	s_add_u32 s70, s30, 0x100
	v_mov_b32_e32 v2, 0
	s_addc_u32 s71, s31, 0
	s_mov_b32 s72, -2
	v_mov_b32_e32 v3, v2
	v_mov_b32_e32 v4, v2
	v_mov_b32_e32 v5, v2
	v_mov_b32_e32 v6, v2
	v_mov_b32_e32 v7, v2
	v_mov_b32_e32 v8, v2
	v_mov_b32_e32 v9, v2
	v_mov_b32_e32 v18, v2
	v_mov_b32_e32 v19, v2
	v_mov_b32_e32 v20, v2
	v_mov_b32_e32 v21, v2
	v_mov_b32_e32 v22, v2
	v_mov_b32_e32 v23, v2
	v_mov_b32_e32 v24, v2
	v_mov_b32_e32 v25, v2
	v_mov_b32_e32 v34, v2
	v_mov_b32_e32 v35, v2
	v_mov_b32_e32 v36, v2
	v_mov_b32_e32 v37, v2
	v_mov_b32_e32 v38, v2
	v_mov_b32_e32 v39, v2
	v_mov_b32_e32 v40, v2
	v_mov_b32_e32 v41, v2
	v_mov_b32_e32 v50, v2
	v_mov_b32_e32 v51, v2
	v_mov_b32_e32 v52, v2
	v_mov_b32_e32 v53, v2
	v_mov_b32_e32 v54, v2
	v_mov_b32_e32 v55, v2
	v_mov_b32_e32 v56, v2
	v_mov_b32_e32 v57, v2
	v_mov_b32_e32 v10, v2
	v_mov_b32_e32 v11, v2
	v_mov_b32_e32 v12, v2
	v_mov_b32_e32 v13, v2
	v_mov_b32_e32 v14, v2
	v_mov_b32_e32 v15, v2
	v_mov_b32_e32 v16, v2
	v_mov_b32_e32 v17, v2
	v_mov_b32_e32 v26, v2
	v_mov_b32_e32 v27, v2
	v_mov_b32_e32 v28, v2
	v_mov_b32_e32 v29, v2
	v_mov_b32_e32 v30, v2
	v_mov_b32_e32 v31, v2
	v_mov_b32_e32 v32, v2
	v_mov_b32_e32 v33, v2
	v_mov_b32_e32 v42, v2
	v_mov_b32_e32 v43, v2
	v_mov_b32_e32 v44, v2
	v_mov_b32_e32 v45, v2
	v_mov_b32_e32 v46, v2
	v_mov_b32_e32 v47, v2
	v_mov_b32_e32 v48, v2
	v_mov_b32_e32 v49, v2
	v_mov_b32_e32 v58, v2
	v_mov_b32_e32 v59, v2
	v_mov_b32_e32 v60, v2
	v_mov_b32_e32 v61, v2
	v_mov_b32_e32 v62, v2
	v_mov_b32_e32 v63, v2
	v_mov_b32_e32 v64, v2
	v_mov_b32_e32 v65, v2
	v_mov_b32_e32 v66, v2
	v_mov_b32_e32 v67, v2
	v_mov_b32_e32 v68, v2
	v_mov_b32_e32 v69, v2
	v_mov_b32_e32 v70, v2
	v_mov_b32_e32 v71, v2
	v_mov_b32_e32 v72, v2
	v_mov_b32_e32 v73, v2
	v_mov_b32_e32 v82, v2
	v_mov_b32_e32 v83, v2
	v_mov_b32_e32 v84, v2
	v_mov_b32_e32 v85, v2
	v_mov_b32_e32 v86, v2
	v_mov_b32_e32 v87, v2
	v_mov_b32_e32 v88, v2
	v_mov_b32_e32 v89, v2
	v_mov_b32_e32 v98, v2
	v_mov_b32_e32 v99, v2
	v_mov_b32_e32 v100, v2
	v_mov_b32_e32 v101, v2
	v_mov_b32_e32 v102, v2
	v_mov_b32_e32 v103, v2
	v_mov_b32_e32 v104, v2
	v_mov_b32_e32 v105, v2
	v_mov_b32_e32 v114, v2
	v_mov_b32_e32 v115, v2
	v_mov_b32_e32 v116, v2
	v_mov_b32_e32 v117, v2
	v_mov_b32_e32 v118, v2
	v_mov_b32_e32 v119, v2
	v_mov_b32_e32 v120, v2
	v_mov_b32_e32 v121, v2
	v_mov_b32_e32 v74, v2
	v_mov_b32_e32 v75, v2
	v_mov_b32_e32 v76, v2
	v_mov_b32_e32 v77, v2
	v_mov_b32_e32 v78, v2
	v_mov_b32_e32 v79, v2
	v_mov_b32_e32 v80, v2
	v_mov_b32_e32 v81, v2
	v_mov_b32_e32 v90, v2
	v_mov_b32_e32 v91, v2
	v_mov_b32_e32 v92, v2
	v_mov_b32_e32 v93, v2
	v_mov_b32_e32 v94, v2
	v_mov_b32_e32 v95, v2
	v_mov_b32_e32 v96, v2
	v_mov_b32_e32 v97, v2
	v_mov_b32_e32 v106, v2
	v_mov_b32_e32 v107, v2
	v_mov_b32_e32 v108, v2
	v_mov_b32_e32 v109, v2
	v_mov_b32_e32 v110, v2
	v_mov_b32_e32 v111, v2
	v_mov_b32_e32 v112, v2
	v_mov_b32_e32 v113, v2
	v_mov_b32_e32 v122, v2
	v_mov_b32_e32 v123, v2
	v_mov_b32_e32 v124, v2
	v_mov_b32_e32 v125, v2
	v_mov_b32_e32 v126, v2
	v_mov_b32_e32 v127, v2
	v_mov_b32_e32 v128, v2
	v_mov_b32_e32 v129, v2
	s_lshl_b32 s98, s69, 8
	s_or_b32 s98, s98, s53
	s_lshl_b32 s99, s68, 8
	s_add_i32 s99, s99, s52
	v_lshl_add_u32 v235, v165, 3, s98
	v_add_u32_e32 v253, s99, v164
	v_lshlrev_b32_e32 v235, 2, v235
	v_lshlrev_b32_e32 v253, 2, v253
	global_load_dwordx4 v[226:229], v235, s[4:5] offset:16
	global_load_dwordx4 v[230:233], v235, s[4:5]
	global_load_dwordx4 v[236:239], v235, s[4:5] offset:528
	global_load_dwordx4 v[240:243], v235, s[4:5] offset:512
	global_load_dword v244, v253, s[12:13]
	global_load_dword v245, v253, s[12:13] offset:64
	global_load_dword v246, v253, s[12:13] offset:128
	global_load_dword v247, v253, s[12:13] offset:192
	global_load_dword v248, v253, s[12:13] offset:512
	global_load_dword v249, v253, s[12:13] offset:576
	global_load_dword v250, v253, s[12:13] offset:640
	global_load_dword v251, v253, s[12:13] offset:704

.LBB0_1102:
	s_lshl_b32 s28, s69, 8
	v_mov_b32_e32 v130, v165
	v_mov_b32_e32 v162, v164
	s_or_b32 s28, s28, s53
	v_cvt_f32_i32_e32 v127, v127
	v_lshl_add_u32 v170, v130, 3, s28
	s_lshl_b32 s28, s68, 8
	s_add_i32 s28, s28, s52
	v_ashrrev_i32_e32 v171, 31, v170
	v_add_u32_e32 v172, s28, v162
	v_lshl_add_u64 v[142:143], v[170:171], 2, s[4:5]
	v_ashrrev_i32_e32 v173, 31, v172
	v_mov_b64_e32 v[130:131], v[226:227]
	v_mov_b64_e32 v[132:133], v[228:229]
	v_mov_b64_e32 v[138:139], v[230:231]
	v_mov_b64_e32 v[140:141], v[232:233]
	v_mov_b64_e32 v[134:135], v[236:237]
	v_mov_b64_e32 v[136:137], v[238:239]
	s_nop 0
	v_mov_b64_e32 v[142:143], v[240:241]
	v_mov_b64_e32 v[144:145], v[242:243]
	v_lshl_add_u64 v[162:163], v[172:173], 2, s[12:13]
	v_mov_b32_e32 v174, v244
	v_cvt_f32_i32_e32 v126, v126
	v_cvt_f32_i32_e32 v129, v129
	v_cvt_f32_i32_e32 v128, v128
	v_cvt_f32_i32_e32 v123, v123
	v_cvt_f32_i32_e32 v122, v122
	v_cvt_f32_i32_e32 v125, v125
	v_cvt_f32_i32_e32 v124, v124
	v_cvt_f32_i32_e32 v119, v119
	v_cvt_f32_i32_e32 v118, v118
	v_cvt_f32_i32_e32 v117, v117
	v_cvt_f32_i32_e32 v116, v116
	v_cvt_f32_i32_e32 v121, v121
	v_cvt_f32_i32_e32 v120, v120
	v_cvt_f32_i32_e32 v177, v115
	v_cvt_f32_i32_e32 v176, v114
	v_lshlrev_b64 v[114:115], 13, v[172:173]
	v_lshl_add_u64 v[114:115], s[10:11], 0, v[114:115]
	v_lshl_add_u64 v[114:115], v[170:171], 1, v[114:115]
	v_cvt_f32_i32_e32 v111, v111
	v_cvt_f32_i32_e32 v110, v110
	v_cvt_f32_i32_e32 v113, v113
	v_cvt_f32_i32_e32 v112, v112
	v_cvt_f32_i32_e32 v107, v107
	v_cvt_f32_i32_e32 v106, v106
	v_cvt_f32_i32_e32 v109, v109
	v_cvt_f32_i32_e32 v108, v108
	v_cvt_f32_i32_e32 v103, v103
	v_cvt_f32_i32_e32 v102, v102
	v_cvt_f32_i32_e32 v105, v105
	v_cvt_f32_i32_e32 v104, v104
	v_cvt_f32_i32_e32 v99, v99
	v_cvt_f32_i32_e32 v98, v98
	v_cvt_f32_i32_e32 v101, v101
	v_cvt_f32_i32_e32 v100, v100
	s_mov_b32 s30, 0x20000
	s_mov_b64 s[28:29], 0x20000
	v_cvt_f32_i32_e32 v95, v95
	v_cvt_f32_i32_e32 v94, v94
	v_cvt_f32_i32_e32 v97, v97
	v_cvt_f32_i32_e32 v96, v96
	v_cvt_f32_i32_e32 v91, v91
	v_cvt_f32_i32_e32 v90, v90
	v_cvt_f32_i32_e32 v93, v93
	v_cvt_f32_i32_e32 v92, v92
	v_cvt_f32_i32_e32 v87, v87
	v_cvt_f32_i32_e32 v86, v86
	v_cvt_f32_i32_e32 v89, v89
	v_cvt_f32_i32_e32 v88, v88
	v_cvt_f32_i32_e32 v83, v83
	v_cvt_f32_i32_e32 v82, v82
	v_cvt_f32_i32_e32 v85, v85
	v_cvt_f32_i32_e32 v84, v84
	v_cvt_f32_i32_e32 v79, v79
	v_cvt_f32_i32_e32 v78, v78
	v_cvt_f32_i32_e32 v81, v81
	v_cvt_f32_i32_e32 v80, v80
	v_cvt_f32_i32_e32 v75, v75
	v_cvt_f32_i32_e32 v74, v74
	v_cvt_f32_i32_e32 v77, v77
	v_cvt_f32_i32_e32 v76, v76
	v_cvt_f32_i32_e32 v71, v71
	v_cvt_f32_i32_e32 v70, v70
	v_cvt_f32_i32_e32 v73, v73
	v_cvt_f32_i32_e32 v72, v72
	v_cvt_f32_i32_e32 v67, v67
	v_cvt_f32_i32_e32 v66, v66
	v_cvt_f32_i32_e32 v69, v69
	v_cvt_f32_i32_e32 v68, v68
	v_cvt_f32_i32_e32 v63, v63
	v_cvt_f32_i32_e32 v62, v62
	v_cvt_f32_i32_e32 v65, v65
	v_cvt_f32_i32_e32 v64, v64
	v_cvt_f32_i32_e32 v59, v59
	v_cvt_f32_i32_e32 v58, v58
	v_cvt_f32_i32_e32 v61, v61
	v_pk_mul_f32 v[124:125], v[132:133], v[124:125]
	v_pk_mul_f32 v[128:129], v[140:141], v[128:129]
	v_pk_mul_f32 v[126:127], v[138:139], v[126:127]
	v_pk_mul_f32 v[122:123], v[130:131], v[122:123]
	v_pk_mul_f32 v[118:119], v[142:143], v[118:119]
	v_pk_mul_f32 v[116:117], v[136:137], v[116:117]
	v_pk_mul_f32 v[120:121], v[144:145], v[120:121]
	v_pk_mul_f32 v[170:171], v[134:135], v[176:177]
	v_pk_mul_f32 v[128:129], v[128:129], v[174:175] op_sel_hi:[1,0]
	v_pk_mul_f32 v[126:127], v[126:127], v[174:175] op_sel_hi:[1,0]
	v_pk_mul_f32 v[124:125], v[124:125], v[174:175] op_sel_hi:[1,0]
	v_pk_mul_f32 v[122:123], v[122:123], v[174:175] op_sel_hi:[1,0]
	v_pk_mul_f32 v[172:173], v[118:119], v[174:175] op_sel_hi:[1,0]
	v_pk_mul_f32 v[176:177], v[116:117], v[174:175] op_sel_hi:[1,0]
	v_cvt_pk_bf16_f32 v116, v126, v127
	v_cvt_pk_bf16_f32 v117, v128, v129
	v_cvt_pk_bf16_f32 v118, v122, v123
	v_cvt_pk_bf16_f32 v119, v124, v125
	v_pk_mul_f32 v[120:121], v[120:121], v[174:175] op_sel_hi:[1,0]
	v_pk_mul_f32 v[170:171], v[170:171], v[174:175] op_sel_hi:[1,0]
	global_store_dwordx4 v[114:115], v[116:119], off
	v_pk_mul_f32 v[112:113], v[140:141], v[112:113]
	v_pk_mul_f32 v[110:111], v[138:139], v[110:111]
	v_cvt_pk_bf16_f32 v116, v172, v173
	v_cvt_pk_bf16_f32 v117, v120, v121
	v_cvt_pk_bf16_f32 v118, v170, v171
	v_cvt_pk_bf16_f32 v119, v176, v177
	global_store_dwordx4 v[114:115], v[116:119], off offset:256
	s_nop 1
	v_mov_b32_e32 v116, v245
	v_add_co_u32_e32 v120, vcc, s30, v114
	v_pk_mul_f32 v[108:109], v[132:133], v[108:109]
	v_pk_mul_f32 v[106:107], v[130:131], v[106:107]
	v_pk_mul_f32 v[104:105], v[144:145], v[104:105]
	v_pk_mul_f32 v[102:103], v[142:143], v[102:103]
	v_pk_mul_f32 v[100:101], v[136:137], v[100:101]
	v_pk_mul_f32 v[98:99], v[134:135], v[98:99]
	v_lshl_add_u64 v[118:119], v[114:115], 0, s[28:29]
	v_addc_co_u32_e32 v121, vcc, 0, v115, vcc
	s_mov_b32 s30, 0x40000
	s_mov_b64 s[28:29], 0x40000
	v_pk_mul_f32 v[96:97], v[140:141], v[96:97]
	v_pk_mul_f32 v[94:95], v[138:139], v[94:95]
	v_pk_mul_f32 v[92:93], v[132:133], v[92:93]
	v_pk_mul_f32 v[90:91], v[130:131], v[90:91]
	v_pk_mul_f32 v[88:89], v[144:145], v[88:89]
	v_pk_mul_f32 v[86:87], v[142:143], v[86:87]
	v_pk_mul_f32 v[84:85], v[136:137], v[84:85]
	v_pk_mul_f32 v[82:83], v[134:135], v[82:83]
	v_pk_mul_f32 v[80:81], v[140:141], v[80:81]
	v_pk_mul_f32 v[78:79], v[138:139], v[78:79]
	v_pk_mul_f32 v[76:77], v[132:133], v[76:77]
	v_pk_mul_f32 v[74:75], v[130:131], v[74:75]
	v_pk_mul_f32 v[72:73], v[144:145], v[72:73]
	v_pk_mul_f32 v[70:71], v[142:143], v[70:71]
	v_pk_mul_f32 v[68:69], v[136:137], v[68:69]
	v_pk_mul_f32 v[66:67], v[134:135], v[66:67]
	v_cvt_f32_i32_e32 v60, v60
	v_cvt_f32_i32_e32 v55, v55
	v_cvt_f32_i32_e32 v54, v54
	v_cvt_f32_i32_e32 v57, v57
	v_cvt_f32_i32_e32 v56, v56
	v_cvt_f32_i32_e32 v51, v51
	v_cvt_f32_i32_e32 v50, v50
	v_cvt_f32_i32_e32 v53, v53
	v_cvt_f32_i32_e32 v52, v52
	v_pk_mul_f32 v[64:65], v[140:141], v[64:65]
	v_pk_mul_f32 v[62:63], v[138:139], v[62:63]
	v_pk_mul_f32 v[60:61], v[132:133], v[60:61]
	v_pk_mul_f32 v[58:59], v[130:131], v[58:59]
	v_pk_mul_f32 v[56:57], v[144:145], v[56:57]
	v_pk_mul_f32 v[54:55], v[142:143], v[54:55]
	v_pk_mul_f32 v[52:53], v[136:137], v[52:53]
	v_pk_mul_f32 v[50:51], v[134:135], v[50:51]
	v_cvt_f32_i32_e32 v47, v47
	v_cvt_f32_i32_e32 v46, v46
	v_cvt_f32_i32_e32 v49, v49
	v_cvt_f32_i32_e32 v48, v48
	v_cvt_f32_i32_e32 v43, v43
	v_cvt_f32_i32_e32 v42, v42
	v_cvt_f32_i32_e32 v45, v45
	v_cvt_f32_i32_e32 v44, v44
	v_cvt_f32_i32_e32 v39, v39
	v_cvt_f32_i32_e32 v38, v38
	v_cvt_f32_i32_e32 v41, v41
	v_cvt_f32_i32_e32 v40, v40
	v_cvt_f32_i32_e32 v35, v35
	v_cvt_f32_i32_e32 v34, v34
	v_cvt_f32_i32_e32 v37, v37
	v_cvt_f32_i32_e32 v36, v36
	v_pk_mul_f32 v[48:49], v[140:141], v[48:49]
	v_pk_mul_f32 v[46:47], v[138:139], v[46:47]
	v_pk_mul_f32 v[44:45], v[132:133], v[44:45]
	v_pk_mul_f32 v[42:43], v[130:131], v[42:43]
	v_pk_mul_f32 v[40:41], v[144:145], v[40:41]
	v_pk_mul_f32 v[38:39], v[142:143], v[38:39]
	v_pk_mul_f32 v[36:37], v[136:137], v[36:37]
	v_pk_mul_f32 v[34:35], v[134:135], v[34:35]
	v_cvt_f32_i32_e32 v31, v31
	v_cvt_f32_i32_e32 v30, v30
	v_cvt_f32_i32_e32 v33, v33
	v_cvt_f32_i32_e32 v32, v32
	v_cvt_f32_i32_e32 v27, v27
	v_cvt_f32_i32_e32 v26, v26
	v_cvt_f32_i32_e32 v29, v29
	v_cvt_f32_i32_e32 v28, v28
	v_cvt_f32_i32_e32 v23, v23
	v_pk_mul_f32 v[112:113], v[112:113], v[116:117] op_sel_hi:[1,0]
	v_pk_mul_f32 v[110:111], v[110:111], v[116:117] op_sel_hi:[1,0]
	v_pk_mul_f32 v[108:109], v[108:109], v[116:117] op_sel_hi:[1,0]
	v_pk_mul_f32 v[106:107], v[106:107], v[116:117] op_sel_hi:[1,0]
	v_pk_mul_f32 v[104:105], v[104:105], v[116:117] op_sel_hi:[1,0]
	v_pk_mul_f32 v[102:103], v[102:103], v[116:117] op_sel_hi:[1,0]
	v_pk_mul_f32 v[122:123], v[100:101], v[116:117] op_sel_hi:[1,0]
	v_pk_mul_f32 v[116:117], v[98:99], v[116:117] op_sel_hi:[1,0]
	v_cvt_pk_bf16_f32 v98, v110, v111
	v_cvt_pk_bf16_f32 v99, v112, v113
	v_cvt_pk_bf16_f32 v100, v106, v107
	v_cvt_pk_bf16_f32 v101, v108, v109
	global_store_dwordx4 v[120:121], v[98:101], off
	v_cvt_f32_i32_e32 v22, v22
	v_cvt_f32_i32_e32 v25, v25
	v_cvt_pk_bf16_f32 v98, v102, v103
	v_cvt_pk_bf16_f32 v99, v104, v105
	v_cvt_pk_bf16_f32 v100, v116, v117
	v_cvt_pk_bf16_f32 v101, v122, v123
	global_store_dwordx4 v[118:119], v[98:101], off offset:256
	s_nop 1
	v_mov_b32_e32 v98, v246
	v_add_co_u32_e32 v102, vcc, s30, v114
	v_lshl_add_u64 v[100:101], v[114:115], 0, s[28:29]
	s_nop 0
	v_addc_co_u32_e32 v103, vcc, 0, v115, vcc
	s_mov_b64 s[28:29], 0x60000
	v_cvt_f32_i32_e32 v24, v24
	v_cvt_f32_i32_e32 v19, v19
	v_cvt_f32_i32_e32 v18, v18
	v_cvt_f32_i32_e32 v21, v21
	v_cvt_f32_i32_e32 v20, v20
	v_pk_mul_f32 v[32:33], v[140:141], v[32:33]
	v_pk_mul_f32 v[30:31], v[138:139], v[30:31]
	v_pk_mul_f32 v[28:29], v[132:133], v[28:29]
	v_pk_mul_f32 v[26:27], v[130:131], v[26:27]
	v_pk_mul_f32 v[24:25], v[144:145], v[24:25]
	v_pk_mul_f32 v[22:23], v[142:143], v[22:23]
	v_pk_mul_f32 v[20:21], v[136:137], v[20:21]
	v_pk_mul_f32 v[18:19], v[134:135], v[18:19]
	v_cvt_f32_i32_e32 v15, v15
	v_cvt_f32_i32_e32 v14, v14
	v_cvt_f32_i32_e32 v17, v17
	v_cvt_f32_i32_e32 v16, v16
	v_cvt_f32_i32_e32 v11, v11
	v_cvt_f32_i32_e32 v10, v10
	v_cvt_f32_i32_e32 v13, v13
	v_cvt_f32_i32_e32 v12, v12
	v_cvt_f32_i32_e32 v7, v7
	v_cvt_f32_i32_e32 v6, v6
	v_cvt_f32_i32_e32 v9, v9
	v_cvt_f32_i32_e32 v8, v8
	v_cvt_f32_i32_e32 v3, v3
	v_cvt_f32_i32_e32 v2, v2
	v_cvt_f32_i32_e32 v5, v5
	v_cvt_f32_i32_e32 v4, v4
	v_pk_mul_f32 v[16:17], v[140:141], v[16:17]
	v_pk_mul_f32 v[14:15], v[138:139], v[14:15]
	v_pk_mul_f32 v[12:13], v[132:133], v[12:13]
	v_pk_mul_f32 v[10:11], v[130:131], v[10:11]
	v_pk_mul_f32 v[8:9], v[144:145], v[8:9]
	v_pk_mul_f32 v[6:7], v[142:143], v[6:7]
	v_pk_mul_f32 v[4:5], v[136:137], v[4:5]
	v_pk_mul_f32 v[2:3], v[134:135], v[2:3]
	v_pk_mul_f32 v[96:97], v[96:97], v[98:99] op_sel_hi:[1,0]
	v_pk_mul_f32 v[94:95], v[94:95], v[98:99] op_sel_hi:[1,0]
	v_pk_mul_f32 v[92:93], v[92:93], v[98:99] op_sel_hi:[1,0]
	v_pk_mul_f32 v[90:91], v[90:91], v[98:99] op_sel_hi:[1,0]
	v_pk_mul_f32 v[88:89], v[88:89], v[98:99] op_sel_hi:[1,0]
	v_pk_mul_f32 v[86:87], v[86:87], v[98:99] op_sel_hi:[1,0]
	v_pk_mul_f32 v[104:105], v[84:85], v[98:99] op_sel_hi:[1,0]
	v_pk_mul_f32 v[98:99], v[82:83], v[98:99] op_sel_hi:[1,0]
	v_cvt_pk_bf16_f32 v82, v94, v95
	v_cvt_pk_bf16_f32 v83, v96, v97
	v_cvt_pk_bf16_f32 v84, v90, v91
	v_cvt_pk_bf16_f32 v85, v92, v93
	global_store_dwordx4 v[102:103], v[82:85], off
	s_nop 1
	v_cvt_pk_bf16_f32 v82, v86, v87
	v_cvt_pk_bf16_f32 v83, v88, v89
	v_cvt_pk_bf16_f32 v84, v98, v99
	v_cvt_pk_bf16_f32 v85, v104, v105
	global_store_dwordx4 v[100:101], v[82:85], off offset:256
	s_nop 1
	v_mov_b32_e32 v82, v247
	v_add_co_u32_e32 v86, vcc, s58, v114
	v_lshl_add_u64 v[84:85], v[114:115], 0, s[28:29]
	s_nop 0
	v_addc_co_u32_e32 v87, vcc, 0, v115, vcc
	v_pk_mul_f32 v[80:81], v[80:81], v[82:83] op_sel_hi:[1,0]
	v_pk_mul_f32 v[78:79], v[78:79], v[82:83] op_sel_hi:[1,0]
	v_pk_mul_f32 v[76:77], v[76:77], v[82:83] op_sel_hi:[1,0]
	v_pk_mul_f32 v[74:75], v[74:75], v[82:83] op_sel_hi:[1,0]
	v_pk_mul_f32 v[72:73], v[72:73], v[82:83] op_sel_hi:[1,0]
	v_pk_mul_f32 v[70:71], v[70:71], v[82:83] op_sel_hi:[1,0]
	v_pk_mul_f32 v[88:89], v[68:69], v[82:83] op_sel_hi:[1,0]
	v_pk_mul_f32 v[82:83], v[66:67], v[82:83] op_sel_hi:[1,0]
	v_cvt_pk_bf16_f32 v66, v78, v79
	v_cvt_pk_bf16_f32 v67, v80, v81
	v_cvt_pk_bf16_f32 v68, v74, v75
	v_cvt_pk_bf16_f32 v69, v76, v77
	global_store_dwordx4 v[86:87], v[66:69], off
	s_nop 1
	v_cvt_pk_bf16_f32 v66, v70, v71
	v_cvt_pk_bf16_f32 v67, v72, v73
	v_cvt_pk_bf16_f32 v68, v82, v83
	v_cvt_pk_bf16_f32 v69, v88, v89
	global_store_dwordx4 v[84:85], v[66:69], off offset:256
	s_nop 1
	v_mov_b32_e32 v66, v248
	v_add_co_u32_e32 v70, vcc, s59, v114
	v_lshl_add_u64 v[68:69], v[114:115], 0, s[18:19]
	s_nop 0
	v_addc_co_u32_e32 v71, vcc, 0, v115, vcc
	v_pk_mul_f32 v[64:65], v[64:65], v[66:67] op_sel_hi:[1,0]
	v_pk_mul_f32 v[62:63], v[62:63], v[66:67] op_sel_hi:[1,0]
	v_pk_mul_f32 v[60:61], v[60:61], v[66:67] op_sel_hi:[1,0]
	v_pk_mul_f32 v[58:59], v[58:59], v[66:67] op_sel_hi:[1,0]
	v_pk_mul_f32 v[56:57], v[56:57], v[66:67] op_sel_hi:[1,0]
	v_pk_mul_f32 v[54:55], v[54:55], v[66:67] op_sel_hi:[1,0]
	v_pk_mul_f32 v[72:73], v[52:53], v[66:67] op_sel_hi:[1,0]
	v_pk_mul_f32 v[66:67], v[50:51], v[66:67] op_sel_hi:[1,0]
	v_cvt_pk_bf16_f32 v50, v62, v63
	v_cvt_pk_bf16_f32 v51, v64, v65
	v_cvt_pk_bf16_f32 v52, v58, v59
	v_cvt_pk_bf16_f32 v53, v60, v61
	global_store_dwordx4 v[70:71], v[50:53], off
	s_nop 1
	v_cvt_pk_bf16_f32 v50, v54, v55
	v_cvt_pk_bf16_f32 v51, v56, v57
	v_cvt_pk_bf16_f32 v52, v66, v67
	v_cvt_pk_bf16_f32 v53, v72, v73
	global_store_dwordx4 v[68:69], v[50:53], off offset:256
	s_nop 1
	v_mov_b32_e32 v50, v249
	v_add_co_u32_e32 v54, vcc, s60, v114
	v_lshl_add_u64 v[52:53], v[114:115], 0, s[20:21]
	s_nop 0
	v_addc_co_u32_e32 v55, vcc, 0, v115, vcc
	v_pk_mul_f32 v[48:49], v[48:49], v[50:51] op_sel_hi:[1,0]
	v_pk_mul_f32 v[46:47], v[46:47], v[50:51] op_sel_hi:[1,0]
	v_pk_mul_f32 v[44:45], v[44:45], v[50:51] op_sel_hi:[1,0]
	v_pk_mul_f32 v[42:43], v[42:43], v[50:51] op_sel_hi:[1,0]
	v_pk_mul_f32 v[40:41], v[40:41], v[50:51] op_sel_hi:[1,0]
	v_pk_mul_f32 v[38:39], v[38:39], v[50:51] op_sel_hi:[1,0]
	v_pk_mul_f32 v[56:57], v[36:37], v[50:51] op_sel_hi:[1,0]
	v_pk_mul_f32 v[50:51], v[34:35], v[50:51] op_sel_hi:[1,0]
	v_cvt_pk_bf16_f32 v34, v46, v47
	v_cvt_pk_bf16_f32 v35, v48, v49
	v_cvt_pk_bf16_f32 v36, v42, v43
	v_cvt_pk_bf16_f32 v37, v44, v45
	global_store_dwordx4 v[54:55], v[34:37], off
	s_nop 1
	v_cvt_pk_bf16_f32 v34, v38, v39
	v_cvt_pk_bf16_f32 v35, v40, v41
	v_cvt_pk_bf16_f32 v36, v50, v51
	v_cvt_pk_bf16_f32 v37, v56, v57
	global_store_dwordx4 v[52:53], v[34:37], off offset:256
	s_nop 1
	v_mov_b32_e32 v34, v250
	v_add_co_u32_e32 v38, vcc, s61, v114
	v_lshl_add_u64 v[36:37], v[114:115], 0, s[22:23]
	s_nop 0
	v_addc_co_u32_e32 v39, vcc, 0, v115, vcc
	s_and_b64 vcc, exec, s[0:1]
	v_pk_mul_f32 v[32:33], v[32:33], v[34:35] op_sel_hi:[1,0]
	v_pk_mul_f32 v[30:31], v[30:31], v[34:35] op_sel_hi:[1,0]
	v_pk_mul_f32 v[28:29], v[28:29], v[34:35] op_sel_hi:[1,0]
	v_pk_mul_f32 v[26:27], v[26:27], v[34:35] op_sel_hi:[1,0]
	v_pk_mul_f32 v[24:25], v[24:25], v[34:35] op_sel_hi:[1,0]
	v_pk_mul_f32 v[22:23], v[22:23], v[34:35] op_sel_hi:[1,0]
	v_pk_mul_f32 v[40:41], v[20:21], v[34:35] op_sel_hi:[1,0]
	v_pk_mul_f32 v[34:35], v[18:19], v[34:35] op_sel_hi:[1,0]
	v_cvt_pk_bf16_f32 v18, v30, v31
	v_cvt_pk_bf16_f32 v19, v32, v33
	v_cvt_pk_bf16_f32 v20, v26, v27
	v_cvt_pk_bf16_f32 v21, v28, v29
	global_store_dwordx4 v[38:39], v[18:21], off
	s_nop 1
	v_cvt_pk_bf16_f32 v18, v22, v23
	v_cvt_pk_bf16_f32 v19, v24, v25
	v_cvt_pk_bf16_f32 v20, v34, v35
	v_cvt_pk_bf16_f32 v21, v40, v41
	global_store_dwordx4 v[36:37], v[18:21], off offset:256
	s_nop 1
	v_mov_b32_e32 v18, v251
	v_add_co_u32_e64 v22, s[0:1], s62, v114
	v_lshl_add_u64 v[20:21], v[114:115], 0, s[24:25]
	s_nop 0
	v_addc_co_u32_e64 v23, s[0:1], 0, v115, s[0:1]
	s_mov_b64 s[0:1], -1
	v_pk_mul_f32 v[16:17], v[16:17], v[18:19] op_sel_hi:[1,0]
	v_pk_mul_f32 v[14:15], v[14:15], v[18:19] op_sel_hi:[1,0]
	v_pk_mul_f32 v[12:13], v[12:13], v[18:19] op_sel_hi:[1,0]
	v_pk_mul_f32 v[10:11], v[10:11], v[18:19] op_sel_hi:[1,0]
	v_pk_mul_f32 v[8:9], v[8:9], v[18:19] op_sel_hi:[1,0]
	v_pk_mul_f32 v[6:7], v[6:7], v[18:19] op_sel_hi:[1,0]
	v_pk_mul_f32 v[24:25], v[4:5], v[18:19] op_sel_hi:[1,0]
	v_pk_mul_f32 v[18:19], v[2:3], v[18:19] op_sel_hi:[1,0]
	v_cvt_pk_bf16_f32 v2, v14, v15
	v_cvt_pk_bf16_f32 v3, v16, v17
	v_cvt_pk_bf16_f32 v4, v10, v11
	v_cvt_pk_bf16_f32 v5, v12, v13
	global_store_dwordx4 v[22:23], v[2:5], off
	s_nop 1
	v_cvt_pk_bf16_f32 v2, v6, v7
	v_cvt_pk_bf16_f32 v3, v8, v9
	v_cvt_pk_bf16_f32 v4, v18, v19
	v_cvt_pk_bf16_f32 v5, v24, v25
	global_store_dwordx4 v[20:21], v[2:5], off offset:256
	s_cbranch_vccnz .LBB0_1087
	s_andn2_b64 vcc, exec, s[8:9]
	s_cbranch_vccnz .LBB0_1086
	s_barrier
	s_branch .LBB0_1086

.LBB0_1950:
	s_add_u32 s75, s38, 0x100
	v_mov_b32_e32 v2, 0
	s_addc_u32 s76, s39, 0
	s_mov_b32 s77, -2
	v_mov_b32_e32 v3, v2
	v_mov_b32_e32 v4, v2
	v_mov_b32_e32 v5, v2
	v_mov_b32_e32 v6, v2
	v_mov_b32_e32 v7, v2
	v_mov_b32_e32 v8, v2
	v_mov_b32_e32 v9, v2
	v_mov_b32_e32 v18, v2
	v_mov_b32_e32 v19, v2
	v_mov_b32_e32 v20, v2
	v_mov_b32_e32 v21, v2
	v_mov_b32_e32 v22, v2
	v_mov_b32_e32 v23, v2
	v_mov_b32_e32 v24, v2
	v_mov_b32_e32 v25, v2
	v_mov_b32_e32 v34, v2
	v_mov_b32_e32 v35, v2
	v_mov_b32_e32 v36, v2
	v_mov_b32_e32 v37, v2
	v_mov_b32_e32 v38, v2
	v_mov_b32_e32 v39, v2
	v_mov_b32_e32 v40, v2
	v_mov_b32_e32 v41, v2
	v_mov_b32_e32 v50, v2
	v_mov_b32_e32 v51, v2
	v_mov_b32_e32 v52, v2
	v_mov_b32_e32 v53, v2
	v_mov_b32_e32 v54, v2
	v_mov_b32_e32 v55, v2
	v_mov_b32_e32 v56, v2
	v_mov_b32_e32 v57, v2
	v_mov_b32_e32 v10, v2
	v_mov_b32_e32 v11, v2
	v_mov_b32_e32 v12, v2
	v_mov_b32_e32 v13, v2
	v_mov_b32_e32 v14, v2
	v_mov_b32_e32 v15, v2
	v_mov_b32_e32 v16, v2
	v_mov_b32_e32 v17, v2
	v_mov_b32_e32 v26, v2
	v_mov_b32_e32 v27, v2
	v_mov_b32_e32 v28, v2
	v_mov_b32_e32 v29, v2
	v_mov_b32_e32 v30, v2
	v_mov_b32_e32 v31, v2
	v_mov_b32_e32 v32, v2
	v_mov_b32_e32 v33, v2
	v_mov_b32_e32 v42, v2
	v_mov_b32_e32 v43, v2
	v_mov_b32_e32 v44, v2
	v_mov_b32_e32 v45, v2
	v_mov_b32_e32 v46, v2
	v_mov_b32_e32 v47, v2
	v_mov_b32_e32 v48, v2
	v_mov_b32_e32 v49, v2
	v_mov_b32_e32 v58, v2
	v_mov_b32_e32 v59, v2
	v_mov_b32_e32 v60, v2
	v_mov_b32_e32 v61, v2
	v_mov_b32_e32 v62, v2
	v_mov_b32_e32 v63, v2
	v_mov_b32_e32 v64, v2
	v_mov_b32_e32 v65, v2
	v_mov_b32_e32 v66, v2
	v_mov_b32_e32 v67, v2
	v_mov_b32_e32 v68, v2
	v_mov_b32_e32 v69, v2
	v_mov_b32_e32 v70, v2
	v_mov_b32_e32 v71, v2
	v_mov_b32_e32 v72, v2
	v_mov_b32_e32 v73, v2
	v_mov_b32_e32 v82, v2
	v_mov_b32_e32 v83, v2
	v_mov_b32_e32 v84, v2
	v_mov_b32_e32 v85, v2
	v_mov_b32_e32 v86, v2
	v_mov_b32_e32 v87, v2
	v_mov_b32_e32 v88, v2
	v_mov_b32_e32 v89, v2
	v_mov_b32_e32 v98, v2
	v_mov_b32_e32 v99, v2
	v_mov_b32_e32 v100, v2
	v_mov_b32_e32 v101, v2
	v_mov_b32_e32 v102, v2
	v_mov_b32_e32 v103, v2
	v_mov_b32_e32 v104, v2
	v_mov_b32_e32 v105, v2
	v_mov_b32_e32 v114, v2
	v_mov_b32_e32 v115, v2
	v_mov_b32_e32 v116, v2
	v_mov_b32_e32 v117, v2
	v_mov_b32_e32 v118, v2
	v_mov_b32_e32 v119, v2
	v_mov_b32_e32 v120, v2
	v_mov_b32_e32 v121, v2
	v_mov_b32_e32 v74, v2
	v_mov_b32_e32 v75, v2
	v_mov_b32_e32 v76, v2
	v_mov_b32_e32 v77, v2
	v_mov_b32_e32 v78, v2
	v_mov_b32_e32 v79, v2
	v_mov_b32_e32 v80, v2
	v_mov_b32_e32 v81, v2
	v_mov_b32_e32 v90, v2
	v_mov_b32_e32 v91, v2
	v_mov_b32_e32 v92, v2
	v_mov_b32_e32 v93, v2
	v_mov_b32_e32 v94, v2
	v_mov_b32_e32 v95, v2
	v_mov_b32_e32 v96, v2
	v_mov_b32_e32 v97, v2
	v_mov_b32_e32 v106, v2
	v_mov_b32_e32 v107, v2
	v_mov_b32_e32 v108, v2
	v_mov_b32_e32 v109, v2
	v_mov_b32_e32 v110, v2
	v_mov_b32_e32 v111, v2
	v_mov_b32_e32 v112, v2
	v_mov_b32_e32 v113, v2
	v_mov_b32_e32 v122, v2
	v_mov_b32_e32 v123, v2
	v_mov_b32_e32 v124, v2
	v_mov_b32_e32 v125, v2
	v_mov_b32_e32 v126, v2
	v_mov_b32_e32 v127, v2
	v_mov_b32_e32 v128, v2
	v_mov_b32_e32 v129, v2
	s_lshl_b32 s98, s74, 8
	s_or_b32 s98, s98, s58
	s_lshl_b32 s99, s73, 8
	s_add_i32 s99, s99, s57
	v_lshl_add_u32 v235, v165, 3, s98
	v_add_u32_e32 v253, s99, v164
	v_lshlrev_b32_e32 v235, 2, v235
	v_lshlrev_b32_e32 v253, 2, v253
	global_load_dwordx4 v[226:229], v235, s[4:5] offset:16
	global_load_dwordx4 v[230:233], v235, s[4:5]
	global_load_dwordx4 v[236:239], v235, s[4:5] offset:528
	global_load_dwordx4 v[240:243], v235, s[4:5] offset:512
	global_load_dword v244, v253, s[12:13]
	global_load_dword v245, v253, s[12:13] offset:64
	global_load_dword v246, v253, s[12:13] offset:128
	global_load_dword v247, v253, s[12:13] offset:192
	global_load_dword v248, v253, s[12:13] offset:512
	global_load_dword v249, v253, s[12:13] offset:576
	global_load_dword v250, v253, s[12:13] offset:640
	global_load_dword v251, v253, s[12:13] offset:704

.LBB0_1954:
	s_lshl_b32 s36, s74, 8
	v_mov_b32_e32 v130, v165
	v_mov_b32_e32 v162, v164
	s_or_b32 s36, s36, s58
	v_cvt_f32_i32_e32 v127, v127
	v_lshl_add_u32 v170, v130, 3, s36
	s_lshl_b32 s36, s73, 8
	s_add_i32 s36, s36, s57
	v_ashrrev_i32_e32 v171, 31, v170
	v_add_u32_e32 v172, s36, v162
	v_lshl_add_u64 v[142:143], v[170:171], 2, s[4:5]
	v_ashrrev_i32_e32 v173, 31, v172
	v_mov_b64_e32 v[130:131], v[226:227]
	v_mov_b64_e32 v[132:133], v[228:229]
	v_mov_b64_e32 v[138:139], v[230:231]
	v_mov_b64_e32 v[140:141], v[232:233]
	v_mov_b64_e32 v[134:135], v[236:237]
	v_mov_b64_e32 v[136:137], v[238:239]
	s_nop 0
	v_mov_b64_e32 v[142:143], v[240:241]
	v_mov_b64_e32 v[144:145], v[242:243]
	v_lshl_add_u64 v[162:163], v[172:173], 2, s[12:13]
	v_mov_b32_e32 v174, v244
	v_cvt_f32_i32_e32 v126, v126
	v_cvt_f32_i32_e32 v129, v129
	v_cvt_f32_i32_e32 v128, v128
	v_cvt_f32_i32_e32 v123, v123
	v_cvt_f32_i32_e32 v122, v122
	v_cvt_f32_i32_e32 v125, v125
	v_cvt_f32_i32_e32 v124, v124
	v_cvt_f32_i32_e32 v119, v119
	v_cvt_f32_i32_e32 v118, v118
	v_cvt_f32_i32_e32 v117, v117
	v_cvt_f32_i32_e32 v116, v116
	v_cvt_f32_i32_e32 v121, v121
	v_cvt_f32_i32_e32 v120, v120
	v_cvt_f32_i32_e32 v177, v115
	v_cvt_f32_i32_e32 v176, v114
	v_lshlrev_b64 v[114:115], 13, v[172:173]
	v_lshl_add_u64 v[114:115], s[10:11], 0, v[114:115]
	v_lshl_add_u64 v[114:115], v[170:171], 1, v[114:115]
	v_cvt_f32_i32_e32 v111, v111
	v_cvt_f32_i32_e32 v110, v110
	v_cvt_f32_i32_e32 v113, v113
	v_cvt_f32_i32_e32 v112, v112
	v_cvt_f32_i32_e32 v107, v107
	v_cvt_f32_i32_e32 v106, v106
	v_cvt_f32_i32_e32 v109, v109
	v_cvt_f32_i32_e32 v108, v108
	v_cvt_f32_i32_e32 v103, v103
	v_cvt_f32_i32_e32 v102, v102
	v_cvt_f32_i32_e32 v105, v105
	v_cvt_f32_i32_e32 v104, v104
	v_cvt_f32_i32_e32 v99, v99
	v_cvt_f32_i32_e32 v98, v98
	v_cvt_f32_i32_e32 v101, v101
	v_cvt_f32_i32_e32 v100, v100
	v_cvt_f32_i32_e32 v95, v95
	v_cvt_f32_i32_e32 v94, v94
	v_cvt_f32_i32_e32 v97, v97
	v_cvt_f32_i32_e32 v96, v96
	v_cvt_f32_i32_e32 v91, v91
	v_cvt_f32_i32_e32 v90, v90
	v_cvt_f32_i32_e32 v93, v93
	v_cvt_f32_i32_e32 v92, v92
	v_cvt_f32_i32_e32 v87, v87
	v_cvt_f32_i32_e32 v86, v86
	v_cvt_f32_i32_e32 v89, v89
	v_cvt_f32_i32_e32 v88, v88
	v_cvt_f32_i32_e32 v83, v83
	v_cvt_f32_i32_e32 v82, v82
	v_cvt_f32_i32_e32 v85, v85
	v_cvt_f32_i32_e32 v84, v84
	v_cvt_f32_i32_e32 v79, v79
	v_cvt_f32_i32_e32 v78, v78
	v_cvt_f32_i32_e32 v81, v81
	v_cvt_f32_i32_e32 v80, v80
	v_cvt_f32_i32_e32 v75, v75
	v_cvt_f32_i32_e32 v74, v74
	v_cvt_f32_i32_e32 v77, v77
	v_cvt_f32_i32_e32 v76, v76
	v_cvt_f32_i32_e32 v71, v71
	v_cvt_f32_i32_e32 v70, v70
	v_cvt_f32_i32_e32 v73, v73
	v_cvt_f32_i32_e32 v72, v72
	v_cvt_f32_i32_e32 v67, v67
	v_cvt_f32_i32_e32 v66, v66
	v_cvt_f32_i32_e32 v69, v69
	v_cvt_f32_i32_e32 v68, v68
	v_cvt_f32_i32_e32 v63, v63
	v_cvt_f32_i32_e32 v62, v62
	v_cvt_f32_i32_e32 v65, v65
	v_cvt_f32_i32_e32 v64, v64
	v_cvt_f32_i32_e32 v59, v59
	v_cvt_f32_i32_e32 v58, v58
	v_cvt_f32_i32_e32 v61, v61
	v_cvt_f32_i32_e32 v60, v60
	v_cvt_f32_i32_e32 v55, v55
	v_pk_mul_f32 v[124:125], v[132:133], v[124:125]
	v_pk_mul_f32 v[128:129], v[140:141], v[128:129]
	v_pk_mul_f32 v[126:127], v[138:139], v[126:127]
	v_pk_mul_f32 v[122:123], v[130:131], v[122:123]
	v_pk_mul_f32 v[118:119], v[142:143], v[118:119]
	v_pk_mul_f32 v[116:117], v[136:137], v[116:117]
	v_pk_mul_f32 v[120:121], v[144:145], v[120:121]
	v_pk_mul_f32 v[170:171], v[134:135], v[176:177]
	v_pk_mul_f32 v[128:129], v[128:129], v[174:175] op_sel_hi:[1,0]
	v_pk_mul_f32 v[126:127], v[126:127], v[174:175] op_sel_hi:[1,0]
	v_pk_mul_f32 v[124:125], v[124:125], v[174:175] op_sel_hi:[1,0]
	v_pk_mul_f32 v[122:123], v[122:123], v[174:175] op_sel_hi:[1,0]
	v_pk_mul_f32 v[172:173], v[118:119], v[174:175] op_sel_hi:[1,0]
	v_pk_mul_f32 v[176:177], v[116:117], v[174:175] op_sel_hi:[1,0]
	v_cvt_pk_bf16_f32 v116, v126, v127
	v_cvt_pk_bf16_f32 v117, v128, v129
	v_cvt_pk_bf16_f32 v118, v122, v123
	v_cvt_pk_bf16_f32 v119, v124, v125
	v_pk_mul_f32 v[120:121], v[120:121], v[174:175] op_sel_hi:[1,0]
	v_pk_mul_f32 v[170:171], v[170:171], v[174:175] op_sel_hi:[1,0]
	global_store_dwordx4 v[114:115], v[116:119], off
	v_pk_mul_f32 v[112:113], v[140:141], v[112:113]
	v_pk_mul_f32 v[110:111], v[138:139], v[110:111]
	v_cvt_pk_bf16_f32 v116, v172, v173
	v_cvt_pk_bf16_f32 v117, v120, v121
	v_cvt_pk_bf16_f32 v118, v170, v171
	v_cvt_pk_bf16_f32 v119, v176, v177
	global_store_dwordx4 v[114:115], v[116:119], off offset:256
	s_nop 1
	v_mov_b32_e32 v116, v245
	v_add_co_u32_e32 v120, vcc, s63, v114
	v_pk_mul_f32 v[108:109], v[132:133], v[108:109]
	v_pk_mul_f32 v[106:107], v[130:131], v[106:107]
	v_pk_mul_f32 v[104:105], v[144:145], v[104:105]
	v_pk_mul_f32 v[102:103], v[142:143], v[102:103]
	v_pk_mul_f32 v[100:101], v[136:137], v[100:101]
	v_pk_mul_f32 v[98:99], v[134:135], v[98:99]
	v_lshl_add_u64 v[118:119], v[114:115], 0, s[18:19]
	v_addc_co_u32_e32 v121, vcc, 0, v115, vcc
	v_pk_mul_f32 v[96:97], v[140:141], v[96:97]
	v_pk_mul_f32 v[94:95], v[138:139], v[94:95]
	v_pk_mul_f32 v[92:93], v[132:133], v[92:93]
	v_pk_mul_f32 v[90:91], v[130:131], v[90:91]
	v_pk_mul_f32 v[88:89], v[144:145], v[88:89]
	v_pk_mul_f32 v[86:87], v[142:143], v[86:87]
	v_pk_mul_f32 v[84:85], v[136:137], v[84:85]
	v_pk_mul_f32 v[82:83], v[134:135], v[82:83]
	v_pk_mul_f32 v[80:81], v[140:141], v[80:81]
	v_pk_mul_f32 v[78:79], v[138:139], v[78:79]
	v_pk_mul_f32 v[76:77], v[132:133], v[76:77]
	v_pk_mul_f32 v[74:75], v[130:131], v[74:75]
	v_pk_mul_f32 v[72:73], v[144:145], v[72:73]
	v_pk_mul_f32 v[70:71], v[142:143], v[70:71]
	v_pk_mul_f32 v[68:69], v[136:137], v[68:69]
	v_pk_mul_f32 v[66:67], v[134:135], v[66:67]
	v_cvt_f32_i32_e32 v54, v54
	v_cvt_f32_i32_e32 v57, v57
	v_cvt_f32_i32_e32 v56, v56
	v_cvt_f32_i32_e32 v51, v51
	v_cvt_f32_i32_e32 v50, v50
	v_cvt_f32_i32_e32 v53, v53
	v_cvt_f32_i32_e32 v52, v52
	v_pk_mul_f32 v[64:65], v[140:141], v[64:65]
	v_pk_mul_f32 v[62:63], v[138:139], v[62:63]
	v_pk_mul_f32 v[60:61], v[132:133], v[60:61]
	v_pk_mul_f32 v[58:59], v[130:131], v[58:59]
	v_pk_mul_f32 v[56:57], v[144:145], v[56:57]
	v_pk_mul_f32 v[54:55], v[142:143], v[54:55]
	v_pk_mul_f32 v[52:53], v[136:137], v[52:53]
	v_pk_mul_f32 v[50:51], v[134:135], v[50:51]
	v_cvt_f32_i32_e32 v47, v47
	v_cvt_f32_i32_e32 v46, v46
	v_cvt_f32_i32_e32 v49, v49
	v_cvt_f32_i32_e32 v48, v48
	v_cvt_f32_i32_e32 v43, v43
	v_cvt_f32_i32_e32 v42, v42
	v_cvt_f32_i32_e32 v45, v45
	v_cvt_f32_i32_e32 v44, v44
	v_cvt_f32_i32_e32 v39, v39
	v_cvt_f32_i32_e32 v38, v38
	v_cvt_f32_i32_e32 v41, v41
	v_cvt_f32_i32_e32 v40, v40
	v_cvt_f32_i32_e32 v35, v35
	v_cvt_f32_i32_e32 v34, v34
	v_cvt_f32_i32_e32 v37, v37
	v_cvt_f32_i32_e32 v36, v36
	v_pk_mul_f32 v[48:49], v[140:141], v[48:49]
	v_pk_mul_f32 v[46:47], v[138:139], v[46:47]
	v_pk_mul_f32 v[44:45], v[132:133], v[44:45]
	v_pk_mul_f32 v[42:43], v[130:131], v[42:43]
	v_pk_mul_f32 v[40:41], v[144:145], v[40:41]
	v_pk_mul_f32 v[38:39], v[142:143], v[38:39]
	v_pk_mul_f32 v[36:37], v[136:137], v[36:37]
	v_pk_mul_f32 v[34:35], v[134:135], v[34:35]
	v_cvt_f32_i32_e32 v31, v31
	v_cvt_f32_i32_e32 v30, v30
	v_cvt_f32_i32_e32 v33, v33
	v_cvt_f32_i32_e32 v32, v32
	v_cvt_f32_i32_e32 v27, v27
	v_cvt_f32_i32_e32 v26, v26
	v_cvt_f32_i32_e32 v29, v29
	v_cvt_f32_i32_e32 v28, v28
	v_cvt_f32_i32_e32 v23, v23
	v_cvt_f32_i32_e32 v22, v22
	v_cvt_f32_i32_e32 v25, v25
	v_cvt_f32_i32_e32 v24, v24
	v_cvt_f32_i32_e32 v19, v19
	v_pk_mul_f32 v[112:113], v[112:113], v[116:117] op_sel_hi:[1,0]
	v_pk_mul_f32 v[110:111], v[110:111], v[116:117] op_sel_hi:[1,0]
	v_pk_mul_f32 v[108:109], v[108:109], v[116:117] op_sel_hi:[1,0]
	v_pk_mul_f32 v[106:107], v[106:107], v[116:117] op_sel_hi:[1,0]
	v_pk_mul_f32 v[104:105], v[104:105], v[116:117] op_sel_hi:[1,0]
	v_pk_mul_f32 v[102:103], v[102:103], v[116:117] op_sel_hi:[1,0]
	v_pk_mul_f32 v[122:123], v[100:101], v[116:117] op_sel_hi:[1,0]
	v_pk_mul_f32 v[116:117], v[98:99], v[116:117] op_sel_hi:[1,0]
	v_cvt_pk_bf16_f32 v98, v110, v111
	v_cvt_pk_bf16_f32 v99, v112, v113
	v_cvt_pk_bf16_f32 v100, v106, v107
	v_cvt_pk_bf16_f32 v101, v108, v109
	global_store_dwordx4 v[120:121], v[98:101], off
	v_cvt_f32_i32_e32 v18, v18
	v_cvt_f32_i32_e32 v21, v21
	v_cvt_pk_bf16_f32 v98, v102, v103
	v_cvt_pk_bf16_f32 v99, v104, v105
	v_cvt_pk_bf16_f32 v100, v116, v117
	v_cvt_pk_bf16_f32 v101, v122, v123
	global_store_dwordx4 v[118:119], v[98:101], off offset:256
	s_nop 1
	v_mov_b32_e32 v98, v246
	v_add_co_u32_e32 v102, vcc, s65, v114
	v_lshl_add_u64 v[100:101], v[114:115], 0, s[20:21]
	s_nop 0
	v_addc_co_u32_e32 v103, vcc, 0, v115, vcc
	v_cvt_f32_i32_e32 v20, v20
	v_pk_mul_f32 v[32:33], v[140:141], v[32:33]
	v_pk_mul_f32 v[30:31], v[138:139], v[30:31]
	v_pk_mul_f32 v[28:29], v[132:133], v[28:29]
	v_pk_mul_f32 v[26:27], v[130:131], v[26:27]
	v_pk_mul_f32 v[24:25], v[144:145], v[24:25]
	v_pk_mul_f32 v[22:23], v[142:143], v[22:23]
	v_pk_mul_f32 v[20:21], v[136:137], v[20:21]
	v_pk_mul_f32 v[18:19], v[134:135], v[18:19]
	v_cvt_f32_i32_e32 v15, v15
	v_cvt_f32_i32_e32 v14, v14
	v_cvt_f32_i32_e32 v17, v17
	v_cvt_f32_i32_e32 v16, v16
	v_cvt_f32_i32_e32 v11, v11
	v_cvt_f32_i32_e32 v10, v10
	v_cvt_f32_i32_e32 v13, v13
	v_cvt_f32_i32_e32 v12, v12
	v_cvt_f32_i32_e32 v7, v7
	v_cvt_f32_i32_e32 v6, v6
	v_cvt_f32_i32_e32 v9, v9
	v_cvt_f32_i32_e32 v8, v8
	v_cvt_f32_i32_e32 v3, v3
	v_cvt_f32_i32_e32 v2, v2
	v_cvt_f32_i32_e32 v5, v5
	v_cvt_f32_i32_e32 v4, v4
	v_pk_mul_f32 v[16:17], v[140:141], v[16:17]
	v_pk_mul_f32 v[14:15], v[138:139], v[14:15]
	v_pk_mul_f32 v[12:13], v[132:133], v[12:13]
	v_pk_mul_f32 v[10:11], v[130:131], v[10:11]
	v_pk_mul_f32 v[8:9], v[144:145], v[8:9]
	v_pk_mul_f32 v[6:7], v[142:143], v[6:7]
	v_pk_mul_f32 v[4:5], v[136:137], v[4:5]
	v_pk_mul_f32 v[2:3], v[134:135], v[2:3]
	v_pk_mul_f32 v[96:97], v[96:97], v[98:99] op_sel_hi:[1,0]
	v_pk_mul_f32 v[94:95], v[94:95], v[98:99] op_sel_hi:[1,0]
	v_pk_mul_f32 v[92:93], v[92:93], v[98:99] op_sel_hi:[1,0]
	v_pk_mul_f32 v[90:91], v[90:91], v[98:99] op_sel_hi:[1,0]
	v_pk_mul_f32 v[88:89], v[88:89], v[98:99] op_sel_hi:[1,0]
	v_pk_mul_f32 v[86:87], v[86:87], v[98:99] op_sel_hi:[1,0]
	v_pk_mul_f32 v[104:105], v[84:85], v[98:99] op_sel_hi:[1,0]
	v_pk_mul_f32 v[98:99], v[82:83], v[98:99] op_sel_hi:[1,0]
	v_cvt_pk_bf16_f32 v82, v94, v95
	v_cvt_pk_bf16_f32 v83, v96, v97
	v_cvt_pk_bf16_f32 v84, v90, v91
	v_cvt_pk_bf16_f32 v85, v92, v93
	global_store_dwordx4 v[102:103], v[82:85], off
	s_nop 1
	v_cvt_pk_bf16_f32 v82, v86, v87
	v_cvt_pk_bf16_f32 v83, v88, v89
	v_cvt_pk_bf16_f32 v84, v98, v99
	v_cvt_pk_bf16_f32 v85, v104, v105
	global_store_dwordx4 v[100:101], v[82:85], off offset:256
	s_nop 1
	v_mov_b32_e32 v82, v247
	v_add_co_u32_e32 v86, vcc, s66, v114
	v_lshl_add_u64 v[84:85], v[114:115], 0, s[22:23]
	s_nop 0
	v_addc_co_u32_e32 v87, vcc, 0, v115, vcc
	v_pk_mul_f32 v[80:81], v[80:81], v[82:83] op_sel_hi:[1,0]
	v_pk_mul_f32 v[78:79], v[78:79], v[82:83] op_sel_hi:[1,0]
	v_pk_mul_f32 v[76:77], v[76:77], v[82:83] op_sel_hi:[1,0]
	v_pk_mul_f32 v[74:75], v[74:75], v[82:83] op_sel_hi:[1,0]
	v_pk_mul_f32 v[72:73], v[72:73], v[82:83] op_sel_hi:[1,0]
	v_pk_mul_f32 v[70:71], v[70:71], v[82:83] op_sel_hi:[1,0]
	v_pk_mul_f32 v[88:89], v[68:69], v[82:83] op_sel_hi:[1,0]
	v_pk_mul_f32 v[82:83], v[66:67], v[82:83] op_sel_hi:[1,0]
	v_cvt_pk_bf16_f32 v66, v78, v79
	v_cvt_pk_bf16_f32 v67, v80, v81
	v_cvt_pk_bf16_f32 v68, v74, v75
	v_cvt_pk_bf16_f32 v69, v76, v77
	global_store_dwordx4 v[86:87], v[66:69], off
	s_nop 1
	v_cvt_pk_bf16_f32 v66, v70, v71
	v_cvt_pk_bf16_f32 v67, v72, v73
	v_cvt_pk_bf16_f32 v68, v82, v83
	v_cvt_pk_bf16_f32 v69, v88, v89
	global_store_dwordx4 v[84:85], v[66:69], off offset:256
	s_nop 1
	v_mov_b32_e32 v66, v248
	v_add_co_u32_e32 v70, vcc, s67, v114
	v_lshl_add_u64 v[68:69], v[114:115], 0, s[24:25]
	s_nop 0
	v_addc_co_u32_e32 v71, vcc, 0, v115, vcc
	v_pk_mul_f32 v[64:65], v[64:65], v[66:67] op_sel_hi:[1,0]
	v_pk_mul_f32 v[62:63], v[62:63], v[66:67] op_sel_hi:[1,0]
	v_pk_mul_f32 v[60:61], v[60:61], v[66:67] op_sel_hi:[1,0]
	v_pk_mul_f32 v[58:59], v[58:59], v[66:67] op_sel_hi:[1,0]
	v_pk_mul_f32 v[56:57], v[56:57], v[66:67] op_sel_hi:[1,0]
	v_pk_mul_f32 v[54:55], v[54:55], v[66:67] op_sel_hi:[1,0]
	v_pk_mul_f32 v[72:73], v[52:53], v[66:67] op_sel_hi:[1,0]
	v_pk_mul_f32 v[66:67], v[50:51], v[66:67] op_sel_hi:[1,0]
	v_cvt_pk_bf16_f32 v50, v62, v63
	v_cvt_pk_bf16_f32 v51, v64, v65
	v_cvt_pk_bf16_f32 v52, v58, v59
	v_cvt_pk_bf16_f32 v53, v60, v61
	global_store_dwordx4 v[70:71], v[50:53], off
	s_nop 1
	v_cvt_pk_bf16_f32 v50, v54, v55
	v_cvt_pk_bf16_f32 v51, v56, v57
	v_cvt_pk_bf16_f32 v52, v66, v67
	v_cvt_pk_bf16_f32 v53, v72, v73
	global_store_dwordx4 v[68:69], v[50:53], off offset:256
	s_nop 1
	v_mov_b32_e32 v50, v249
	v_add_co_u32_e32 v54, vcc, s68, v114
	v_lshl_add_u64 v[52:53], v[114:115], 0, s[26:27]
	s_nop 0
	v_addc_co_u32_e32 v55, vcc, 0, v115, vcc
	v_pk_mul_f32 v[48:49], v[48:49], v[50:51] op_sel_hi:[1,0]
	v_pk_mul_f32 v[46:47], v[46:47], v[50:51] op_sel_hi:[1,0]
	v_pk_mul_f32 v[44:45], v[44:45], v[50:51] op_sel_hi:[1,0]
	v_pk_mul_f32 v[42:43], v[42:43], v[50:51] op_sel_hi:[1,0]
	v_pk_mul_f32 v[40:41], v[40:41], v[50:51] op_sel_hi:[1,0]
	v_pk_mul_f32 v[38:39], v[38:39], v[50:51] op_sel_hi:[1,0]
	v_pk_mul_f32 v[56:57], v[36:37], v[50:51] op_sel_hi:[1,0]
	v_pk_mul_f32 v[50:51], v[34:35], v[50:51] op_sel_hi:[1,0]
	v_cvt_pk_bf16_f32 v34, v46, v47
	v_cvt_pk_bf16_f32 v35, v48, v49
	v_cvt_pk_bf16_f32 v36, v42, v43
	v_cvt_pk_bf16_f32 v37, v44, v45
	global_store_dwordx4 v[54:55], v[34:37], off
	s_nop 1
	v_cvt_pk_bf16_f32 v34, v38, v39
	v_cvt_pk_bf16_f32 v35, v40, v41
	v_cvt_pk_bf16_f32 v36, v50, v51
	v_cvt_pk_bf16_f32 v37, v56, v57
	global_store_dwordx4 v[52:53], v[34:37], off offset:256
	s_nop 1
	v_mov_b32_e32 v34, v250
	v_add_co_u32_e32 v38, vcc, s69, v114
	v_lshl_add_u64 v[36:37], v[114:115], 0, s[28:29]
	s_nop 0
	v_addc_co_u32_e32 v39, vcc, 0, v115, vcc
	s_and_b64 vcc, exec, s[0:1]
	v_pk_mul_f32 v[32:33], v[32:33], v[34:35] op_sel_hi:[1,0]
	v_pk_mul_f32 v[30:31], v[30:31], v[34:35] op_sel_hi:[1,0]
	v_pk_mul_f32 v[28:29], v[28:29], v[34:35] op_sel_hi:[1,0]
	v_pk_mul_f32 v[26:27], v[26:27], v[34:35] op_sel_hi:[1,0]
	v_pk_mul_f32 v[24:25], v[24:25], v[34:35] op_sel_hi:[1,0]
	v_pk_mul_f32 v[22:23], v[22:23], v[34:35] op_sel_hi:[1,0]
	v_pk_mul_f32 v[40:41], v[20:21], v[34:35] op_sel_hi:[1,0]
	v_pk_mul_f32 v[34:35], v[18:19], v[34:35] op_sel_hi:[1,0]
	v_cvt_pk_bf16_f32 v18, v30, v31
	v_cvt_pk_bf16_f32 v19, v32, v33
	v_cvt_pk_bf16_f32 v20, v26, v27
	v_cvt_pk_bf16_f32 v21, v28, v29
	global_store_dwordx4 v[38:39], v[18:21], off
	s_nop 1
	v_cvt_pk_bf16_f32 v18, v22, v23
	v_cvt_pk_bf16_f32 v19, v24, v25
	v_cvt_pk_bf16_f32 v20, v34, v35
	v_cvt_pk_bf16_f32 v21, v40, v41
	global_store_dwordx4 v[36:37], v[18:21], off offset:256
	s_nop 1
	v_mov_b32_e32 v18, v251
	v_add_co_u32_e64 v22, s[0:1], s70, v114
	v_lshl_add_u64 v[20:21], v[114:115], 0, s[30:31]
	s_nop 0
	v_addc_co_u32_e64 v23, s[0:1], 0, v115, s[0:1]
	s_mov_b64 s[0:1], -1
	v_pk_mul_f32 v[16:17], v[16:17], v[18:19] op_sel_hi:[1,0]
	v_pk_mul_f32 v[14:15], v[14:15], v[18:19] op_sel_hi:[1,0]
	v_pk_mul_f32 v[12:13], v[12:13], v[18:19] op_sel_hi:[1,0]
	v_pk_mul_f32 v[10:11], v[10:11], v[18:19] op_sel_hi:[1,0]
	v_pk_mul_f32 v[8:9], v[8:9], v[18:19] op_sel_hi:[1,0]
	v_pk_mul_f32 v[6:7], v[6:7], v[18:19] op_sel_hi:[1,0]
	v_pk_mul_f32 v[24:25], v[4:5], v[18:19] op_sel_hi:[1,0]
	v_pk_mul_f32 v[18:19], v[2:3], v[18:19] op_sel_hi:[1,0]
	v_cvt_pk_bf16_f32 v2, v14, v15
	v_cvt_pk_bf16_f32 v3, v16, v17
	v_cvt_pk_bf16_f32 v4, v10, v11
	v_cvt_pk_bf16_f32 v5, v12, v13
	global_store_dwordx4 v[22:23], v[2:5], off
	s_nop 1
	v_cvt_pk_bf16_f32 v2, v6, v7
	v_cvt_pk_bf16_f32 v3, v8, v9
	v_cvt_pk_bf16_f32 v4, v18, v19
	v_cvt_pk_bf16_f32 v5, v24, v25
	global_store_dwordx4 v[20:21], v[2:5], off offset:256
	s_cbranch_vccnz .LBB0_1939
	s_andn2_b64 vcc, exec, s[8:9]
	s_cbranch_vccnz .LBB0_1938
	s_barrier
	s_branch .LBB0_1938
